# v63 + layer-2 mixer weight transposes (W_rin, W_rout) moved from the G_din phase tail to the idle workgroups of the FFN-in1 partial last round
# baseline (speedup 1.0000x reference)
.LBB0_835:
.LBB0_847:
	s_cmp_gt_i32 s63, 10
	s_cselect_b64 s[2:3], -1, 0
	s_and_b64 s[4:5], s[6:7], s[2:3]
	s_andn2_b64 vcc, exec, s[4:5]
	s_cbranch_vccnz .LBB0_892
	s_mov_b32 s4, s1
	s_waitcnt lgkmcnt(0)
	s_mov_b32 s5, s28
	s_mov_b32 s6, s76
	s_waitcnt vmcnt(0)
	v_mbcnt_lo_u32_b32 v0, -1, 0
	v_mbcnt_hi_u32_b32 v0, -1, v0
	s_waitcnt vmcnt(0)
	s_lshl_b32 s4, s4, 6
	v_sub_u32_e32 v0, 0, v0
	v_cmp_eq_u32_e32 vcc, s4, v0
	s_barrier
	s_and_saveexec_b64 s[4:5], vcc
	s_cbranch_execz .LBB0_891
	v_mov_b32_e32 v0, s79
	s_waitcnt vmcnt(0) expcnt(0) lgkmcnt(0)
	ds_read_b32 v2, v0
	ds_read_b32 v0, v0 offset:4
	s_waitcnt lgkmcnt(1)
	v_cmp_ne_u32_e32 vcc, 0, v2
	s_cbranch_vccnz .LBB0_862
	v_readlane_b32 s6, v255, 0
	v_readlane_b32 s7, v255, 1
	s_load_dwordx2 s[10:11], s[6:7], 0x4
	s_add_u32 s6, s30, 0x1000
	s_addc_u32 s7, s31, 0
	s_add_u32 s8, s30, 0x1100
	s_addc_u32 s9, s31, 0
	s_waitcnt lgkmcnt(0)
	s_mul_i32 s20, s10, s28
	s_add_u32 s10, s30, 0x1200
	s_mul_i32 s20, s20, s11
	s_addc_u32 s11, s31, 0
	s_add_u32 s12, s30, 0x1300
	s_addc_u32 s13, s31, 0
	s_mov_b32 s21, 1
	v_mov_b32_e32 v16, 0
	s_branch .LBB0_852

.LBB0_1261:
	s_waitcnt vmcnt(0)
	s_barrier
	s_cmp_lt_u32 s76, 44
	s_cbranch_scc1 .Lbgm_skip
	s_nop 4
	v_writelane_b32 v254, s2, 0
	v_writelane_b32 v254, s3, 1
	v_writelane_b32 v254, s4, 2
	v_writelane_b32 v254, s5, 3
	v_writelane_b32 v254, s8, 4
	v_writelane_b32 v254, s9, 5
	v_writelane_b32 v254, s10, 6
	v_writelane_b32 v254, s11, 7
	v_writelane_b32 v254, s12, 8
	v_writelane_b32 v254, s13, 9
	v_writelane_b32 v254, s14, 10
	v_writelane_b32 v254, s15, 11
	v_writelane_b32 v254, s16, 12
	v_writelane_b32 v254, s17, 13
	v_writelane_b32 v254, s18, 14
	v_writelane_b32 v254, s19, 15
	v_writelane_b32 v254, s20, 16
	v_writelane_b32 v254, s21, 17
	v_writelane_b32 v254, s22, 18
	v_writelane_b32 v254, s23, 19
	v_writelane_b32 v254, s24, 20
	v_writelane_b32 v254, s25, 21
	v_writelane_b32 v254, s26, 22
	v_writelane_b32 v254, s27, 23
	v_writelane_b32 v254, s29, 24
	v_writelane_b32 v254, s33, 25
	v_writelane_b32 v254, s34, 26
	v_writelane_b32 v254, s35, 27
	v_writelane_b32 v254, s36, 28
	v_writelane_b32 v254, s37, 29
	v_writelane_b32 v254, s38, 30
	s_lshl_b32 s12, s76, 3
	s_addk_i32 s12, 0xfea0
	s_mov_b64 s[2:3], 0
	s_mov_b32 s4, s1
	v_mbcnt_lo_u32_b32 v5, -1, 0
	v_mbcnt_hi_u32_b32 v5, -1, v5
	s_mov_b32 s5, s76
	v_lshl_add_u32 v0, s4, 6, v5
	s_mov_b32 s13, s28
	v_readlane_b32 s8, v255, 2
	v_readfirstlane_b32 s4, v0
	v_readlane_b32 s9, v255, 3
	s_ashr_i32 s11, s4, 6
	v_and_b32_e32 v10, 63, v5
	s_mov_b64 s[4:5], s[8:9]
	s_and_b64 vcc, exec, s[2:3]
	s_cbranch_vccnz .LBB0_841_m
	s_add_i32 s10, s12, s11
	s_cmpk_gt_i32 s10, 0xbff
	s_cbranch_scc1 .LBB0_841_m
	s_load_dwordx2 s[16:17], s[4:5], 0xa8
	s_load_dwordx2 s[18:19], s[8:9], 0xf0
	v_lshlrev_b32_e32 v1, 2, v5
	s_lshl_b32 s4, s11, 14
	v_and_b32_e32 v6, 0x7c, v1
	v_lshlrev_b32_e32 v1, 3, v10
	s_add_i32 s8, s4, 0
	v_mov_b32_e32 v7, 0
	v_and_b32_e32 v1, 56, v1
	s_waitcnt lgkmcnt(0)
	v_lshl_add_u64 v[2:3], s[16:17], 0, v[6:7]
	v_add_u32_e32 v4, s8, v6
	v_lshrrev_b32_e32 v11, 3, v10
	v_lshlrev_b32_e32 v6, 1, v1
	s_lshl_b32 s14, s13, 3
	v_lshrrev_b32_e32 v0, 5, v10
	v_mul_u32_u24_e32 v8, 0x84, v1
	v_lshl_add_u64 v[6:7], s[18:19], 0, v[6:7]
	s_mov_b64 s[4:5], 0x2a00000
	v_lshlrev_b32_e32 v1, 2, v11
	s_addk_i32 s14, 0xfea0
	s_movk_i32 s15, 0x84
	v_lshl_add_u64 v[6:7], v[6:7], 0, s[4:5]
	v_add3_u32 v12, s8, v8, v1
	v_or_b32_e32 v13, 8, v11
	v_or_b32_e32 v14, 16, v11
	v_or_b32_e32 v15, 24, v11
	v_mov_b32_e32 v1, v0
	s_movk_i32 s16, 0x6000
	s_movk_i32 s17, 0x7fff
	s_mov_b32 s18, 0xffff0000

.LBB0_841_m:
	v_readlane_b32 s8, v255, 2
	v_readlane_b32 s9, v255, 3
	s_mov_b64 s[4:5], s[8:9]
	s_and_b64 vcc, exec, s[2:3]
	s_cbranch_vccnz .Lbgm_exit
	s_add_i32 s10, s12, s11
	s_cmpk_gt_i32 s10, 0x3ff
	s_cbranch_scc1 .Lbgm_exit
	s_load_dwordx2 s[2:3], s[4:5], 0xb0
	s_load_dwordx2 s[14:15], s[8:9], 0xf0
	v_lshlrev_b32_e32 v1, 2, v5
	s_lshl_b32 s4, s11, 14
	v_and_b32_e32 v6, 0x7c, v1
	v_lshlrev_b32_e32 v1, 3, v10
	s_add_i32 s4, s4, 0
	v_mov_b32_e32 v7, 0
	v_and_b32_e32 v1, 56, v1
	s_waitcnt lgkmcnt(0)
	v_lshl_add_u64 v[2:3], s[2:3], 0, v[6:7]
	v_add_u32_e32 v4, s4, v6
	v_lshrrev_b32_e32 v5, 3, v10
	v_lshlrev_b32_e32 v6, 1, v1
	s_lshl_b32 s8, s13, 3
	v_lshrrev_b32_e32 v0, 5, v10
	v_mul_u32_u24_e32 v8, 0x84, v1
	v_lshl_add_u64 v[6:7], s[14:15], 0, v[6:7]
	s_mov_b64 s[2:3], 0x3600000
	v_lshlrev_b32_e32 v1, 2, v5
	s_addk_i32 s8, 0xfea0
	s_movk_i32 s9, 0x84
	v_lshl_add_u64 v[6:7], v[6:7], 0, s[2:3]
	v_add3_u32 v10, s4, v8, v1
	v_or_b32_e32 v11, 8, v5
	v_or_b32_e32 v12, 16, v5
	v_or_b32_e32 v13, 24, v5
	v_mov_b32_e32 v1, v0
	s_movk_i32 s11, 0x7fff
	s_mov_b32 s12, 0xffff0000

.Lbgm_exit:
	v_readlane_b32 s2, v254, 0
	v_readlane_b32 s3, v254, 1
	v_readlane_b32 s4, v254, 2
	v_readlane_b32 s5, v254, 3
	v_readlane_b32 s8, v254, 4
	v_readlane_b32 s9, v254, 5
	v_readlane_b32 s10, v254, 6
	v_readlane_b32 s11, v254, 7
	v_readlane_b32 s12, v254, 8
	v_readlane_b32 s13, v254, 9
	v_readlane_b32 s14, v254, 10
	v_readlane_b32 s15, v254, 11
	v_readlane_b32 s16, v254, 12
	v_readlane_b32 s17, v254, 13
	v_readlane_b32 s18, v254, 14
	v_readlane_b32 s19, v254, 15
	v_readlane_b32 s20, v254, 16
	v_readlane_b32 s21, v254, 17
	v_readlane_b32 s22, v254, 18
	v_readlane_b32 s23, v254, 19
	v_readlane_b32 s24, v254, 20
	v_readlane_b32 s25, v254, 21
	v_readlane_b32 s26, v254, 22
	v_readlane_b32 s27, v254, 23
	v_readlane_b32 s29, v254, 24
	v_readlane_b32 s33, v254, 25
	v_readlane_b32 s34, v254, 26
	v_readlane_b32 s35, v254, 27
	v_readlane_b32 s36, v254, 28
	v_readlane_b32 s37, v254, 29
	v_readlane_b32 s38, v254, 30
	s_nop 4
.Lbgm_skip:
.LBB0_1262:
	s_cmp_gt_i32 s63, 14
	s_cselect_b64 s[2:3], -1, 0
	s_and_b64 s[4:5], s[4:5], s[2:3]
	s_andn2_b64 vcc, exec, s[4:5]
	s_cbranch_vccnz .LBB0_1307
	s_mov_b32 s4, s1
	s_waitcnt lgkmcnt(0)
	s_mov_b32 s5, s28
	s_mov_b32 s6, s76
	s_waitcnt vmcnt(0)
	v_mbcnt_lo_u32_b32 v0, -1, 0
	v_mbcnt_hi_u32_b32 v0, -1, v0
	s_waitcnt vmcnt(0)
	s_lshl_b32 s4, s4, 6
	v_sub_u32_e32 v0, 0, v0
	v_cmp_eq_u32_e32 vcc, s4, v0
	s_barrier
	s_and_saveexec_b64 s[4:5], vcc
	s_cbranch_execz .LBB0_1306
	v_mov_b32_e32 v0, s79
	s_waitcnt vmcnt(0) expcnt(0) lgkmcnt(0)
	ds_read_b32 v2, v0
	ds_read_b32 v0, v0 offset:4
	s_waitcnt lgkmcnt(1)
	v_cmp_ne_u32_e32 vcc, 0, v2
	s_cbranch_vccnz .LBB0_1277
	v_readlane_b32 s6, v255, 0
	v_readlane_b32 s7, v255, 1
	s_load_dwordx2 s[10:11], s[6:7], 0x4
	s_add_u32 s6, s30, 0x1000
	s_addc_u32 s7, s31, 0
	s_add_u32 s8, s30, 0x1100
	s_addc_u32 s9, s31, 0
	s_waitcnt lgkmcnt(0)
	s_mul_i32 s20, s10, s28
	s_add_u32 s10, s30, 0x1200
	s_mul_i32 s20, s20, s11
	s_addc_u32 s11, s31, 0
	s_add_u32 s12, s30, 0x1300
	s_addc_u32 s13, s31, 0
	s_mov_b32 s21, 1
	v_mov_b32_e32 v16, 0
	s_branch .LBB0_1267
